# v16 + fp8 K-loop MFMAs in boustrophedon order (one shared operand between consecutive MFMAs)
# baseline (speedup 1.0000x reference)
.LBB0_1420:
	ds_read_b128 v[146:149], v138
	ds_read_b128 v[150:153], v138 offset:1024
	ds_read_b128 v[154:157], v138 offset:2048
	ds_read_b128 v[158:161], v138 offset:3072
	ds_read_b128 v[162:165], v139
	ds_read_b128 v[166:169], v139 offset:1024
	ds_read_b128 v[170:173], v139 offset:2048
	ds_read_b128 v[174:177], v139 offset:3072
	s_add_i32 s14, s73, 0xfff40080
	s_cmp_eq_u32 s60, s75
	s_cselect_b32 s76, s71, s14
	s_cselect_b32 s78, s72, s74
	s_or_b32 s77, s76, 0x80
	s_add_i32 s14, s73, 0xfffc0000
	s_mov_b32 m0, s61
	ds_read_b128 v[178:181], v140
	ds_read_b128 v[182:185], v140 offset:1024
	ds_read_b128 v[186:189], v140 offset:2048
	ds_read_b128 v[190:193], v140 offset:3072
	ds_read_b128 v[194:197], v140 offset:4096
	ds_read_b128 v[198:201], v140 offset:5120
	ds_read_b128 v[202:205], v140 offset:6144
	ds_read_b128 v[206:209], v140 offset:7168
	buffer_load_dwordx4 v136, s[16:19], s14 offen lds
	s_mov_b32 m0, s62
	s_nop 0
	buffer_load_dwordx4 v136, s[16:19], s73 offen lds
	s_waitcnt vmcnt(8) lgkmcnt(0)
	s_setprio 1
	s_barrier
	v_mfma_f32_16x16x128_f8f6f4 v[118:121], v[146:153], v[178:185], v[118:121]
	v_mfma_f32_16x16x128_f8f6f4 v[114:117], v[154:161], v[178:185], v[114:117]
	v_mfma_f32_16x16x128_f8f6f4 v[126:129], v[162:169], v[178:185], v[126:129]
	v_mfma_f32_16x16x128_f8f6f4 v[122:125], v[170:177], v[178:185], v[122:125]
	v_mfma_f32_16x16x128_f8f6f4 v[98:101], v[170:177], v[186:193], v[98:101]
	v_mfma_f32_16x16x128_f8f6f4 v[106:109], v[162:169], v[186:193], v[106:109]
	v_mfma_f32_16x16x128_f8f6f4 v[102:105], v[154:161], v[186:193], v[102:105]
	v_mfma_f32_16x16x128_f8f6f4 v[110:113], v[146:153], v[186:193], v[110:113]
	v_mfma_f32_16x16x128_f8f6f4 v[210:213], v[146:153], v[194:201], v[94:97]
	v_mfma_f32_16x16x128_f8f6f4 v[214:217], v[154:161], v[194:201], v[86:89]
	v_mfma_f32_16x16x128_f8f6f4 v[178:181], v[162:169], v[194:201], v[90:93]
	v_mfma_f32_16x16x128_f8f6f4 v[182:185], v[170:177], v[194:201], v[82:85]
	v_mfma_f32_16x16x128_f8f6f4 v[190:193], v[170:177], v[202:209], v[66:69]
	v_mfma_f32_16x16x128_f8f6f4 v[186:189], v[162:169], v[202:209], v[74:77]
	v_mfma_f32_16x16x128_f8f6f4 v[222:225], v[154:161], v[202:209], v[70:73]
	v_mfma_f32_16x16x128_f8f6f4 v[218:221], v[146:153], v[202:209], v[78:81]
	s_setprio 0
	s_barrier
	s_mov_b32 m0, s31
	s_mov_b32 s14, s18
	s_mov_b32 s15, s19
	s_nop 1
	ds_read_b128 v[66:69], v140 offset:16384
	ds_read_b128 v[70:73], v140 offset:17408
	ds_read_b128 v[74:77], v140 offset:18432
	ds_read_b128 v[78:81], v140 offset:19456
	ds_read_b128 v[82:85], v140 offset:20480
	ds_read_b128 v[86:89], v140 offset:21504
	ds_read_b128 v[90:93], v140 offset:22528
	ds_read_b128 v[94:97], v140 offset:23552
	buffer_load_dwordx4 v137, s[12:15], s78 offen lds
	s_mov_b32 m0, s46
	s_add_i32 s79, s78, 0x40000
	buffer_load_dwordx4 v137, s[12:15], s79 offen lds
	s_mov_b32 m0, s47
	s_add_i32 s79, s78, 0x80000
	buffer_load_dwordx4 v137, s[12:15], s79 offen lds
	s_mov_b32 m0, s48
	s_add_i32 s79, s78, 0xc0000
	buffer_load_dwordx4 v137, s[12:15], s79 offen lds
	s_mov_b32 m0, s30
	s_add_i32 s79, s76, 0x40000
	buffer_load_dwordx4 v136, s[16:19], s76 offen lds
	s_mov_b32 m0, s49
	s_nop 0
	buffer_load_dwordx4 v136, s[16:19], s79 offen lds
	s_waitcnt vmcnt(8) lgkmcnt(0)
	s_setprio 1
	s_barrier
	v_mfma_f32_16x16x128_f8f6f4 v[62:65], v[146:153], v[66:73], v[62:65]
	v_mfma_f32_16x16x128_f8f6f4 v[54:57], v[154:161], v[66:73], v[54:57]
	v_mfma_f32_16x16x128_f8f6f4 v[58:61], v[162:169], v[66:73], v[58:61]
	v_mfma_f32_16x16x128_f8f6f4 v[50:53], v[170:177], v[66:73], v[50:53]
	v_mfma_f32_16x16x128_f8f6f4 v[238:241], v[170:177], v[74:81], v[34:37]
	v_mfma_f32_16x16x128_f8f6f4 v[42:45], v[162:169], v[74:81], v[42:45]
	v_mfma_f32_16x16x128_f8f6f4 v[202:205], v[154:161], v[74:81], v[38:41]
	v_mfma_f32_16x16x128_f8f6f4 v[46:49], v[146:153], v[74:81], v[46:49]
	v_mfma_f32_16x16x128_f8f6f4 v[206:209], v[146:153], v[82:89], v[30:33]
	v_mfma_f32_16x16x128_f8f6f4 v[226:229], v[154:161], v[82:89], v[22:25]
	v_mfma_f32_16x16x128_f8f6f4 v[242:245], v[162:169], v[82:89], v[26:29]
	v_mfma_f32_16x16x128_f8f6f4 v[246:249], v[170:177], v[82:89], v[18:21]
	v_mfma_f32_16x16x128_f8f6f4 v[130:133], v[170:177], v[90:97], v[2:5]
	v_mfma_f32_16x16x128_f8f6f4 v[250:253], v[162:169], v[90:97], v[10:13]
	v_mfma_f32_16x16x128_f8f6f4 v[234:237], v[154:161], v[90:97], v[6:9]
	v_mfma_f32_16x16x128_f8f6f4 v[230:233], v[146:153], v[90:97], v[14:17]
	s_setprio 0
	s_barrier
	s_nop 4
	ds_read_b128 v[2:5], v141
	ds_read_b128 v[6:9], v141 offset:1024
	ds_read_b128 v[146:149], v141 offset:2048
	ds_read_b128 v[150:153], v141 offset:3072
	ds_read_b128 v[154:157], v142
	ds_read_b128 v[158:161], v142 offset:1024
	ds_read_b128 v[162:165], v142 offset:2048
	ds_read_b128 v[166:169], v142 offset:3072
	s_mov_b32 m0, s50
	s_add_i32 s79, s76, 0x80000
	ds_read_b128 v[10:13], v140 offset:32768
	ds_read_b128 v[14:17], v140 offset:33792
	ds_read_b128 v[18:21], v140 offset:34816
	ds_read_b128 v[22:25], v140 offset:35840
	ds_read_b128 v[26:29], v140 offset:36864
	ds_read_b128 v[30:33], v140 offset:37888
	ds_read_b128 v[34:37], v140 offset:38912
	ds_read_b128 v[38:41], v140 offset:39936
	buffer_load_dwordx4 v136, s[16:19], s79 offen lds
	s_mov_b32 m0, s51
	s_add_i32 s79, s76, 0xc0000
	buffer_load_dwordx4 v136, s[16:19], s79 offen lds
	s_waitcnt vmcnt(8) lgkmcnt(0)
	s_setprio 1
	s_barrier
	v_mfma_f32_16x16x128_f8f6f4 v[118:121], v[2:9], v[10:17], v[118:121]
	v_mfma_f32_16x16x128_f8f6f4 v[114:117], v[146:153], v[10:17], v[114:117]
	v_mfma_f32_16x16x128_f8f6f4 v[126:129], v[154:161], v[10:17], v[126:129]
	v_mfma_f32_16x16x128_f8f6f4 v[122:125], v[162:169], v[10:17], v[122:125]
	v_mfma_f32_16x16x128_f8f6f4 v[98:101], v[162:169], v[18:25], v[98:101]
	v_mfma_f32_16x16x128_f8f6f4 v[106:109], v[154:161], v[18:25], v[106:109]
	v_mfma_f32_16x16x128_f8f6f4 v[102:105], v[146:153], v[18:25], v[102:105]
	v_mfma_f32_16x16x128_f8f6f4 v[110:113], v[2:9], v[18:25], v[110:113]
	v_mfma_f32_16x16x128_f8f6f4 v[94:97], v[2:9], v[26:33], v[210:213]
	v_mfma_f32_16x16x128_f8f6f4 v[86:89], v[146:153], v[26:33], v[214:217]
	v_mfma_f32_16x16x128_f8f6f4 v[90:93], v[154:161], v[26:33], v[178:181]
	v_mfma_f32_16x16x128_f8f6f4 v[82:85], v[162:169], v[26:33], v[182:185]
	v_mfma_f32_16x16x128_f8f6f4 v[66:69], v[162:169], v[34:41], v[190:193]
	v_mfma_f32_16x16x128_f8f6f4 v[74:77], v[154:161], v[34:41], v[186:189]
	v_mfma_f32_16x16x128_f8f6f4 v[70:73], v[146:153], v[34:41], v[222:225]
	v_mfma_f32_16x16x128_f8f6f4 v[78:81], v[2:9], v[34:41], v[218:221]
	s_setprio 0
	s_barrier
	s_mov_b32 m0, s54
	s_or_b32 s79, s78, 0x80
	ds_read_b128 v[170:173], v140 offset:49152
	ds_read_b128 v[174:177], v140 offset:50176
	ds_read_b128 v[178:181], v140 offset:51200
	ds_read_b128 v[182:185], v140 offset:52224
	ds_read_b128 v[186:189], v140 offset:53248
	ds_read_b128 v[190:193], v140 offset:54272
	ds_read_b128 v[194:197], v140 offset:55296
	ds_read_b128 v[198:201], v140 offset:56320
	buffer_load_dwordx4 v137, s[12:15], s79 offen lds
	s_add_i32 s79, s78, 0x40080
	s_mov_b32 m0, s55
	s_add_i32 s76, s76, 0x40080
	buffer_load_dwordx4 v137, s[12:15], s79 offen lds
	s_add_i32 s79, s78, 0x80080
	s_mov_b32 m0, s58
	s_add_i32 s78, s78, 0xc0080
	buffer_load_dwordx4 v137, s[12:15], s79 offen lds
	s_mov_b32 m0, s59
	s_nop 0
	buffer_load_dwordx4 v137, s[12:15], s78 offen lds
	s_mov_b32 m0, s56
	s_nop 0
	buffer_load_dwordx4 v136, s[16:19], s77 offen lds
	s_mov_b32 m0, s57
	s_nop 0
	buffer_load_dwordx4 v136, s[16:19], s76 offen lds
	s_waitcnt vmcnt(8) lgkmcnt(0)
	s_setprio 1
	s_barrier
	v_mfma_f32_16x16x128_f8f6f4 v[62:65], v[2:9], v[170:177], v[62:65]
	v_mfma_f32_16x16x128_f8f6f4 v[46:49], v[2:9], v[178:185], v[46:49]
	v_mfma_f32_16x16x128_f8f6f4 v[30:33], v[2:9], v[186:193], v[206:209]
	v_mfma_f32_16x16x128_f8f6f4 v[14:17], v[2:9], v[194:201], v[230:233]
	v_mfma_f32_16x16x128_f8f6f4 v[6:9], v[146:153], v[194:201], v[234:237]
	v_mfma_f32_16x16x128_f8f6f4 v[22:25], v[146:153], v[186:193], v[226:229]
	v_mfma_f32_16x16x128_f8f6f4 v[38:41], v[146:153], v[178:185], v[202:205]
	v_mfma_f32_16x16x128_f8f6f4 v[54:57], v[146:153], v[170:177], v[54:57]
	v_mfma_f32_16x16x128_f8f6f4 v[58:61], v[154:161], v[170:177], v[58:61]
	v_mfma_f32_16x16x128_f8f6f4 v[42:45], v[154:161], v[178:185], v[42:45]
	v_mfma_f32_16x16x128_f8f6f4 v[26:29], v[154:161], v[186:193], v[242:245]
	v_mfma_f32_16x16x128_f8f6f4 v[10:13], v[154:161], v[194:201], v[250:253]
	v_mfma_f32_16x16x128_f8f6f4 v[2:5], v[162:169], v[194:201], v[130:133]
	v_mfma_f32_16x16x128_f8f6f4 v[18:21], v[162:169], v[186:193], v[246:249]
	v_mfma_f32_16x16x128_f8f6f4 v[34:37], v[162:169], v[178:185], v[238:241]
	v_mfma_f32_16x16x128_f8f6f4 v[50:53], v[162:169], v[170:177], v[50:53]
	s_setprio 0
	s_barrier
	s_add_i32 s75, s75, 2
	s_addk_i32 s73, 0x100
	s_addk_i32 s74, 0x100
	s_cmp_ge_i32 s75, s25
	s_cbranch_scc0 .LBB0_1420
	s_and_b64 vcc, exec, s[44:45]
	s_cbranch_vccz .LBB0_1423

.LBB0_1567:
	ds_read_b128 v[134:137], v225
	ds_read_b128 v[138:141], v225 offset:1024
	ds_read_b128 v[142:145], v225 offset:2048
	ds_read_b128 v[146:149], v225 offset:3072
	ds_read_b128 v[150:153], v226
	ds_read_b128 v[154:157], v226 offset:1024
	ds_read_b128 v[158:161], v226 offset:2048
	ds_read_b128 v[162:165], v226 offset:3072
	s_add_i32 s18, s8, 0xffdfc080
	s_cmp_eq_u32 s71, s55
	s_cselect_b32 s56, s6, s18
	s_cselect_b32 s91, s7, s9
	s_or_b32 s57, s56, 0x80
	s_add_i32 s18, s8, 0xfff54000
	s_mov_b32 m0, s72
	ds_read_b128 v[166:169], v227
	ds_read_b128 v[170:173], v227 offset:1024
	ds_read_b128 v[174:177], v227 offset:2048
	ds_read_b128 v[178:181], v227 offset:3072
	ds_read_b128 v[182:185], v227 offset:4096
	ds_read_b128 v[186:189], v227 offset:5120
	ds_read_b128 v[190:193], v227 offset:6144
	ds_read_b128 v[194:197], v227 offset:7168
	buffer_load_dwordx4 v223, s[12:15], s18 offen lds
	s_mov_b32 m0, s75
	s_nop 0
	buffer_load_dwordx4 v223, s[12:15], s8 offen lds
	s_waitcnt vmcnt(8) lgkmcnt(0)
	s_setprio 1
	s_barrier
	v_mfma_f32_16x16x128_f8f6f4 v[126:129], v[134:141], v[166:173], v[126:129]
	v_mfma_f32_16x16x128_f8f6f4 v[122:125], v[142:149], v[166:173], v[122:125]
	v_mfma_f32_16x16x128_f8f6f4 v[110:113], v[150:157], v[166:173], v[110:113]
	v_mfma_f32_16x16x128_f8f6f4 v[102:105], v[158:165], v[166:173], v[102:105]
	v_mfma_f32_16x16x128_f8f6f4 v[170:173], v[158:165], v[174:181], v[86:89]
	v_mfma_f32_16x16x128_f8f6f4 v[166:169], v[150:157], v[174:181], v[94:97]
	v_mfma_f32_16x16x128_f8f6f4 v[114:117], v[142:149], v[174:181], v[114:117]
	v_mfma_f32_16x16x128_f8f6f4 v[118:121], v[134:141], v[174:181], v[118:121]
	v_mfma_f32_16x16x128_f8f6f4 v[106:109], v[134:141], v[182:189], v[106:109]
	v_mfma_f32_16x16x128_f8f6f4 v[98:101], v[142:149], v[182:189], v[98:101]
	v_mfma_f32_16x16x128_f8f6f4 v[174:177], v[150:157], v[182:189], v[78:81]
	v_mfma_f32_16x16x128_f8f6f4 v[178:181], v[158:165], v[182:189], v[74:77]
	v_mfma_f32_16x16x128_f8f6f4 v[186:189], v[158:165], v[190:197], v[66:69]
	v_mfma_f32_16x16x128_f8f6f4 v[182:185], v[150:157], v[190:197], v[70:73]
	v_mfma_f32_16x16x128_f8f6f4 v[202:205], v[142:149], v[190:197], v[82:85]
	v_mfma_f32_16x16x128_f8f6f4 v[198:201], v[134:141], v[190:197], v[90:93]
	s_setprio 0
	s_barrier
	s_mov_b32 m0, s27
	s_mov_b32 s18, s14
	s_mov_b32 s19, s15
	s_nop 1
	ds_read_b128 v[66:69], v227 offset:16384
	ds_read_b128 v[70:73], v227 offset:17408
	ds_read_b128 v[74:77], v227 offset:18432
	ds_read_b128 v[78:81], v227 offset:19456
	ds_read_b128 v[82:85], v227 offset:20480
	ds_read_b128 v[86:89], v227 offset:21504
	ds_read_b128 v[90:93], v227 offset:22528
	ds_read_b128 v[94:97], v227 offset:23552
	buffer_load_dwordx4 v224, s[16:19], s91 offen lds
	s_mov_b32 m0, s30
	s_add_i32 s92, s91, 0xac000
	buffer_load_dwordx4 v224, s[16:19], s92 offen lds
	s_mov_b32 m0, s31
	s_add_i32 s92, s91, 0x158000
	buffer_load_dwordx4 v224, s[16:19], s92 offen lds
	s_mov_b32 m0, s51
	s_add_i32 s92, s91, 0x204000
	buffer_load_dwordx4 v224, s[16:19], s92 offen lds
	s_mov_b32 m0, s25
	s_add_i32 s92, s56, 0xac000
	buffer_load_dwordx4 v223, s[12:15], s56 offen lds
	s_mov_b32 m0, s58
	s_nop 0
	buffer_load_dwordx4 v223, s[12:15], s92 offen lds
	s_waitcnt vmcnt(8) lgkmcnt(0)
	s_setprio 1
	s_barrier
	v_mfma_f32_16x16x128_f8f6f4 v[62:65], v[134:141], v[66:73], v[62:65]
	v_mfma_f32_16x16x128_f8f6f4 v[58:61], v[142:149], v[66:73], v[58:61]
	v_mfma_f32_16x16x128_f8f6f4 v[214:217], v[150:157], v[66:73], v[46:49]
	v_mfma_f32_16x16x128_f8f6f4 v[218:221], v[158:165], v[66:73], v[38:41]
	v_mfma_f32_16x16x128_f8f6f4 v[238:241], v[158:165], v[74:81], v[22:25]
	v_mfma_f32_16x16x128_f8f6f4 v[234:237], v[150:157], v[74:81], v[30:33]
	v_mfma_f32_16x16x128_f8f6f4 v[50:53], v[142:149], v[74:81], v[50:53]
	v_mfma_f32_16x16x128_f8f6f4 v[54:57], v[134:141], v[74:81], v[54:57]
	v_mfma_f32_16x16x128_f8f6f4 v[190:193], v[134:141], v[82:89], v[42:45]
	v_mfma_f32_16x16x128_f8f6f4 v[194:197], v[142:149], v[82:89], v[34:37]
	v_mfma_f32_16x16x128_f8f6f4 v[242:245], v[150:157], v[82:89], v[14:17]
	v_mfma_f32_16x16x128_f8f6f4 v[246:249], v[158:165], v[82:89], v[10:13]
	v_mfma_f32_16x16x128_f8f6f4 v[130:133], v[158:165], v[90:97], v[2:5]
	v_mfma_f32_16x16x128_f8f6f4 v[250:253], v[150:157], v[90:97], v[6:9]
	v_mfma_f32_16x16x128_f8f6f4 v[210:213], v[142:149], v[90:97], v[18:21]
	v_mfma_f32_16x16x128_f8f6f4 v[206:209], v[134:141], v[90:97], v[26:29]
	s_setprio 0
	s_barrier
	s_nop 4
	ds_read_b128 v[2:5], v228
	ds_read_b128 v[6:9], v228 offset:1024
	ds_read_b128 v[10:13], v228 offset:2048
	ds_read_b128 v[14:17], v228 offset:3072
	ds_read_b128 v[134:137], v229
	ds_read_b128 v[138:141], v229 offset:1024
	ds_read_b128 v[142:145], v229 offset:2048
	ds_read_b128 v[146:149], v229 offset:3072
	s_mov_b32 m0, s59
	s_add_i32 s92, s56, 0x158000
	ds_read_b128 v[18:21], v227 offset:32768
	ds_read_b128 v[22:25], v227 offset:33792
	ds_read_b128 v[26:29], v227 offset:34816
	ds_read_b128 v[30:33], v227 offset:35840
	ds_read_b128 v[34:37], v227 offset:36864
	ds_read_b128 v[38:41], v227 offset:37888
	ds_read_b128 v[42:45], v227 offset:38912
	ds_read_b128 v[46:49], v227 offset:39936
	buffer_load_dwordx4 v223, s[12:15], s92 offen lds
	s_mov_b32 m0, s60
	s_add_i32 s92, s56, 0x204000
	buffer_load_dwordx4 v223, s[12:15], s92 offen lds
	s_waitcnt vmcnt(8) lgkmcnt(0)
	s_setprio 1
	s_barrier
	v_mfma_f32_16x16x128_f8f6f4 v[126:129], v[2:9], v[18:25], v[126:129]
	v_mfma_f32_16x16x128_f8f6f4 v[122:125], v[10:17], v[18:25], v[122:125]
	v_mfma_f32_16x16x128_f8f6f4 v[110:113], v[134:141], v[18:25], v[110:113]
	v_mfma_f32_16x16x128_f8f6f4 v[102:105], v[142:149], v[18:25], v[102:105]
	v_mfma_f32_16x16x128_f8f6f4 v[86:89], v[142:149], v[26:33], v[170:173]
	v_mfma_f32_16x16x128_f8f6f4 v[94:97], v[134:141], v[26:33], v[166:169]
	v_mfma_f32_16x16x128_f8f6f4 v[114:117], v[10:17], v[26:33], v[114:117]
	v_mfma_f32_16x16x128_f8f6f4 v[118:121], v[2:9], v[26:33], v[118:121]
	v_mfma_f32_16x16x128_f8f6f4 v[106:109], v[2:9], v[34:41], v[106:109]
	v_mfma_f32_16x16x128_f8f6f4 v[98:101], v[10:17], v[34:41], v[98:101]
	v_mfma_f32_16x16x128_f8f6f4 v[78:81], v[134:141], v[34:41], v[174:177]
	v_mfma_f32_16x16x128_f8f6f4 v[74:77], v[142:149], v[34:41], v[178:181]
	v_mfma_f32_16x16x128_f8f6f4 v[66:69], v[142:149], v[42:49], v[186:189]
	v_mfma_f32_16x16x128_f8f6f4 v[70:73], v[134:141], v[42:49], v[182:185]
	v_mfma_f32_16x16x128_f8f6f4 v[82:85], v[10:17], v[42:49], v[202:205]
	v_mfma_f32_16x16x128_f8f6f4 v[90:93], v[2:9], v[42:49], v[198:201]
	s_setprio 0
	s_barrier
	s_mov_b32 m0, s63
	s_or_b32 s92, s91, 0x80
	ds_read_b128 v[150:153], v227 offset:49152
	ds_read_b128 v[154:157], v227 offset:50176
	ds_read_b128 v[158:161], v227 offset:51200
	ds_read_b128 v[162:165], v227 offset:52224
	ds_read_b128 v[166:169], v227 offset:53248
	ds_read_b128 v[170:173], v227 offset:54272
	ds_read_b128 v[174:177], v227 offset:55296
	ds_read_b128 v[178:181], v227 offset:56320
	buffer_load_dwordx4 v224, s[16:19], s92 offen lds
	s_add_i32 s92, s91, 0xac080
	s_mov_b32 m0, s64
	s_add_i32 s56, s56, 0xac080
	buffer_load_dwordx4 v224, s[16:19], s92 offen lds
	s_add_i32 s92, s91, 0x158080
	s_mov_b32 m0, s67
	s_add_i32 s91, s91, 0x204080
	buffer_load_dwordx4 v224, s[16:19], s92 offen lds
	s_mov_b32 m0, s68
	s_nop 0
	buffer_load_dwordx4 v224, s[16:19], s91 offen lds
	s_mov_b32 m0, s65
	s_nop 0
	buffer_load_dwordx4 v223, s[12:15], s57 offen lds
	s_mov_b32 m0, s66
	s_nop 0
	buffer_load_dwordx4 v223, s[12:15], s56 offen lds
	s_waitcnt vmcnt(8) lgkmcnt(0)
	s_setprio 1
	s_barrier
	v_mfma_f32_16x16x128_f8f6f4 v[62:65], v[2:9], v[150:157], v[62:65]
	v_mfma_f32_16x16x128_f8f6f4 v[54:57], v[2:9], v[158:165], v[54:57]
	v_mfma_f32_16x16x128_f8f6f4 v[42:45], v[2:9], v[166:173], v[190:193]
	v_mfma_f32_16x16x128_f8f6f4 v[26:29], v[2:9], v[174:181], v[206:209]
	v_mfma_f32_16x16x128_f8f6f4 v[18:21], v[10:17], v[174:181], v[210:213]
	v_mfma_f32_16x16x128_f8f6f4 v[34:37], v[10:17], v[166:173], v[194:197]
	v_mfma_f32_16x16x128_f8f6f4 v[50:53], v[10:17], v[158:165], v[50:53]
	v_mfma_f32_16x16x128_f8f6f4 v[58:61], v[10:17], v[150:157], v[58:61]
	v_mfma_f32_16x16x128_f8f6f4 v[46:49], v[134:141], v[150:157], v[214:217]
	v_mfma_f32_16x16x128_f8f6f4 v[30:33], v[134:141], v[158:165], v[234:237]
	v_mfma_f32_16x16x128_f8f6f4 v[14:17], v[134:141], v[166:173], v[242:245]
	v_mfma_f32_16x16x128_f8f6f4 v[6:9], v[134:141], v[174:181], v[250:253]
	v_mfma_f32_16x16x128_f8f6f4 v[2:5], v[142:149], v[174:181], v[130:133]
	v_mfma_f32_16x16x128_f8f6f4 v[10:13], v[142:149], v[166:173], v[246:249]
	v_mfma_f32_16x16x128_f8f6f4 v[22:25], v[142:149], v[158:165], v[238:241]
	v_mfma_f32_16x16x128_f8f6f4 v[38:41], v[142:149], v[150:157], v[218:221]
	s_setprio 0
	s_barrier
	s_add_i32 s55, s55, 2
	s_addk_i32 s8, 0x100
	s_addk_i32 s9, 0x100
	s_cmp_ge_i32 s55, s3
	s_cbranch_scc0 .LBB0_1567
	v_pk_mul_f32 v[208:209], v[128:129], s[50:51] op_sel_hi:[1,0]
	v_pk_mul_f32 v[210:211], v[126:127], s[50:51] op_sel_hi:[1,0]
	v_pk_mul_f32 v[212:213], v[124:125], s[50:51] op_sel_hi:[1,0]
	v_pk_mul_f32 v[122:123], v[122:123], s[50:51] op_sel_hi:[1,0]
	v_pk_mul_f32 v[220:221], v[112:113], s[50:51] op_sel_hi:[1,0]
	v_pk_mul_f32 v[218:219], v[110:111], s[50:51] op_sel_hi:[1,0]
	v_pk_mul_f32 v[216:217], v[104:105], s[50:51] op_sel_hi:[1,0]
	v_pk_mul_f32 v[214:215], v[102:103], s[50:51] op_sel_hi:[1,0]
	v_pk_mul_f32 v[206:207], v[120:121], s[50:51] op_sel_hi:[1,0]
	v_pk_mul_f32 v[146:147], v[118:119], s[50:51] op_sel_hi:[1,0]
	v_pk_mul_f32 v[204:205], v[116:117], s[50:51] op_sel_hi:[1,0]
	v_pk_mul_f32 v[144:145], v[114:115], s[50:51] op_sel_hi:[1,0]
	v_pk_mul_f32 v[148:149], v[96:97], s[50:51] op_sel_hi:[1,0]
	v_pk_mul_f32 v[154:155], v[94:95], s[50:51] op_sel_hi:[1,0]
	v_pk_mul_f32 v[202:203], v[88:89], s[50:51] op_sel_hi:[1,0]
	v_pk_mul_f32 v[200:201], v[86:87], s[50:51] op_sel_hi:[1,0]
	v_pk_mul_f32 v[198:199], v[108:109], s[50:51] op_sel_hi:[1,0]
	v_pk_mul_f32 v[152:153], v[106:107], s[50:51] op_sel_hi:[1,0]
	v_pk_mul_f32 v[196:197], v[100:101], s[50:51] op_sel_hi:[1,0]
	v_pk_mul_f32 v[150:151], v[98:99], s[50:51] op_sel_hi:[1,0]
	v_pk_mul_f32 v[156:157], v[80:81], s[50:51] op_sel_hi:[1,0]
	v_pk_mul_f32 v[162:163], v[78:79], s[50:51] op_sel_hi:[1,0]
	v_pk_mul_f32 v[194:195], v[76:77], s[50:51] op_sel_hi:[1,0]
	v_pk_mul_f32 v[192:193], v[74:75], s[50:51] op_sel_hi:[1,0]
	v_pk_mul_f32 v[190:191], v[92:93], s[50:51] op_sel_hi:[1,0]
	v_pk_mul_f32 v[160:161], v[90:91], s[50:51] op_sel_hi:[1,0]
	v_pk_mul_f32 v[188:189], v[84:85], s[50:51] op_sel_hi:[1,0]
	v_pk_mul_f32 v[158:159], v[82:83], s[50:51] op_sel_hi:[1,0]
	v_pk_mul_f32 v[164:165], v[72:73], s[50:51] op_sel_hi:[1,0]
	v_pk_mul_f32 v[170:171], v[70:71], s[50:51] op_sel_hi:[1,0]
	v_pk_mul_f32 v[186:187], v[68:69], s[50:51] op_sel_hi:[1,0]
	v_pk_mul_f32 v[184:185], v[66:67], s[50:51] op_sel_hi:[1,0]
	v_pk_mul_f32 v[182:183], v[64:65], s[50:51] op_sel_hi:[1,0]
	v_pk_mul_f32 v[168:169], v[62:63], s[50:51] op_sel_hi:[1,0]
	v_pk_mul_f32 v[180:181], v[60:61], s[50:51] op_sel_hi:[1,0]
	v_pk_mul_f32 v[166:167], v[58:59], s[50:51] op_sel_hi:[1,0]
	v_pk_mul_f32 v[172:173], v[48:49], s[50:51] op_sel_hi:[1,0]
	v_pk_mul_f32 v[178:179], v[46:47], s[50:51] op_sel_hi:[1,0]
	v_pk_mul_f32 v[176:177], v[40:41], s[50:51] op_sel_hi:[1,0]
	v_pk_mul_f32 v[174:175], v[38:39], s[50:51] op_sel_hi:[1,0]
	v_pk_mul_f32 v[142:143], v[56:57], s[50:51] op_sel_hi:[1,0]
	v_pk_mul_f32 v[140:141], v[54:55], s[50:51] op_sel_hi:[1,0]
	v_pk_mul_f32 v[138:139], v[52:53], s[50:51] op_sel_hi:[1,0]
	v_pk_mul_f32 v[134:135], v[50:51], s[50:51] op_sel_hi:[1,0]
	v_pk_mul_f32 v[136:137], v[32:33], s[50:51] op_sel_hi:[1,0]
	v_pk_mul_f32 v[128:129], v[30:31], s[50:51] op_sel_hi:[1,0]
	v_pk_mul_f32 v[126:127], v[24:25], s[50:51] op_sel_hi:[1,0]
	v_pk_mul_f32 v[124:125], v[22:23], s[50:51] op_sel_hi:[1,0]
	v_pk_mul_f32 v[102:103], v[44:45], s[50:51] op_sel_hi:[1,0]
	v_pk_mul_f32 v[100:101], v[42:43], s[50:51] op_sel_hi:[1,0]
	v_pk_mul_f32 v[98:99], v[36:37], s[50:51] op_sel_hi:[1,0]
	v_pk_mul_f32 v[94:95], v[34:35], s[50:51] op_sel_hi:[1,0]
	v_pk_mul_f32 v[96:97], v[16:17], s[50:51] op_sel_hi:[1,0]
	v_pk_mul_f32 v[92:93], v[14:15], s[50:51] op_sel_hi:[1,0]
	v_pk_mul_f32 v[90:91], v[12:13], s[50:51] op_sel_hi:[1,0]
	v_pk_mul_f32 v[88:89], v[10:11], s[50:51] op_sel_hi:[1,0]
	v_pk_mul_f32 v[86:87], v[28:29], s[50:51] op_sel_hi:[1,0]
	v_pk_mul_f32 v[84:85], v[26:27], s[50:51] op_sel_hi:[1,0]
	v_pk_mul_f32 v[82:83], v[20:21], s[50:51] op_sel_hi:[1,0]
	v_pk_mul_f32 v[78:79], v[18:19], s[50:51] op_sel_hi:[1,0]
	v_pk_mul_f32 v[80:81], v[8:9], s[50:51] op_sel_hi:[1,0]
	v_pk_mul_f32 v[76:77], v[6:7], s[50:51] op_sel_hi:[1,0]
	v_pk_mul_f32 v[74:75], v[4:5], s[50:51] op_sel_hi:[1,0]
	v_pk_mul_f32 v[72:73], v[2:3], s[50:51] op_sel_hi:[1,0]
	s_and_b64 vcc, exec, s[48:49]
	s_cbranch_vccz .LBB0_1570
